# norm phases: g/shift/scale loads for j=1..7 hoisted (24 loads in flight, one round trip instead of 8 per row); SGU lng/lnb loads hoisted to item header
# baseline (speedup 1.0000x reference)
; #define LAS __attribute__((address_space(3)))
; __device__ __forceinline__ unsigned pk2(float lo, float hi) { unsigned r; asm("v_cvt_pk_bf16_f32 %0, %1, %2" : "=v"(r) : "v"(lo), "v"(hi)); return r; }
; __device__ __forceinline__ float bf_lo(unsigned u) { return __uint_as_float(u << 16); }
; __device__ __forceinline__ float bf_hi(unsigned u) { return __uint_as_float(u & 0xffff0000u); }
; __device__ __forceinline__ void phase_sgu(const Params& P, LAS unsigned char* lds, int layer_i) {
;     ...
;         for (int i = 0; i < 4; ++i) { const int n = tid + 512 * i, row = n >> 4, ch = n & 15;
;             *(LAS u32x4*)(lds + SG_A + off_b(row, ch)) = *(const u32x4*)(wsb + ((size_t)g * 128 + row) * 128 + ch * 8); }
;         __syncthreads();
; #pragma unroll
;         for (int i = 0; i < 8; ++i) { const int n = tid + 512 * i, row = n >> 5, cc = n & 31, c0 = g * 256 + cc * 8;
;             const u32x4 v = gvr[i];
;             const float mu = st[2 * row], rs = st[2 * row + 1];
;             const f32x4 g0 = *(const f32x4*)(lng + c0), g1 = *(const f32x4*)(lng + c0 + 4), b0 = *(const f32x4*)(lnb + c0), b1 = *(const f32x4*)(lnb + c0 + 4);
;             u32x4 o;
;             o.x = pk2((bf_lo(v.x) - mu) * rs * g0.x + b0.x, (bf_hi(v.x) - mu) * rs * g0.y + b0.y); o.y = pk2((bf_lo(v.y) - mu) * rs * g0.z + b0.z, (bf_hi(v.y) - mu) * rs * g0.w + b0.w);
;             o.z = pk2((bf_lo(v.z) - mu) * rs * g1.x + b1.x, (bf_hi(v.z) - mu) * rs * g1.y + b1.y); o.w = pk2((bf_lo(v.w) - mu) * rs * g1.z + b1.z, (bf_hi(v.w) - mu) * rs * g1.w + b1.w);
;             *(LAS u32x4*)(lds + SG_B + (cc >> 4) * 32768 + off_b(row, cc & 15)) = o; }
.LBB0_107:
	s_or_b64 exec, exec, s[12:13]
	s_lshl_b32 s30, s2, 7
	s_waitcnt lgkmcnt(0)
	s_lshl_b32 s4, s2, 8
	s_add_i32 s5, 0, 0x20800
	v_lshlrev_b32_e32 v51, 16, v46
	v_and_b32_e32 v46, 0xffff0000, v46
	s_lshl_b32 s12, s4, 1
	s_mov_b32 s13, s31
	s_add_i32 s16, s16, s62
	s_cmpk_gt_i32 s16, 0x3ff
	s_waitcnt vmcnt(0) lgkmcnt(0)
	ds_write_b128 v211, v[82:85]
	ds_write_b128 v212, v[86:89]
	ds_write_b128 v213, v[90:93]
	ds_write_b128 v214, v[94:97]
	v_or_b32_e32 v22, s4, v187
	v_lshlrev_b32_e32 v50, 2, v22
	v_lshlrev_b32_e32 v22, 3, v138
	v_add_u32_e32 v22, s5, v22
	s_waitcnt lgkmcnt(0)
	s_barrier
	ds_read_b64 v[52:53], v22
	v_mov_b32_e32 v22, v100
	v_mov_b32_e32 v23, v101
	v_mov_b32_e32 v24, v102
	v_mov_b32_e32 v25, v103
	v_mov_b32_e32 v34, v104
	v_mov_b32_e32 v35, v105
	v_mov_b32_e32 v36, v106
	v_mov_b32_e32 v37, v107
	v_mov_b32_e32 v30, v108
	v_mov_b32_e32 v31, v109
	v_mov_b32_e32 v32, v110
	v_mov_b32_e32 v33, v111
	v_mov_b32_e32 v38, v112
	v_mov_b32_e32 v39, v113
	v_mov_b32_e32 v40, v114
	v_mov_b32_e32 v41, v115
	s_waitcnt lgkmcnt(0)
	v_sub_f32_e32 v51, v51, v52
	v_sub_f32_e32 v46, v46, v52
	v_mul_f32_e32 v51, v53, v51
	v_mul_f32_e32 v46, v53, v46
	s_waitcnt vmcnt(0)
	v_fma_f32 v51, v51, v34, v38
	v_fma_f32 v46, v46, v35, v39
	v_cvt_pk_bf16_f32 v46, v51, v46
	v_lshlrev_b32_e32 v51, 16, v47
	v_and_b32_e32 v47, 0xffff0000, v47
	v_sub_f32_e32 v51, v51, v52
	v_sub_f32_e32 v47, v47, v52
	v_mul_f32_e32 v51, v53, v51
	v_mul_f32_e32 v47, v53, v47
	v_fma_f32 v51, v51, v36, v40
	v_fma_f32 v47, v47, v37, v41
	v_cvt_pk_bf16_f32 v47, v51, v47
	v_lshlrev_b32_e32 v51, 16, v48
	v_and_b32_e32 v48, 0xffff0000, v48
	v_sub_f32_e32 v51, v51, v52
	v_sub_f32_e32 v48, v48, v52
	v_mul_f32_e32 v51, v53, v51
	v_mul_f32_e32 v48, v53, v48
	v_fma_f32 v51, v51, v22, v30
	v_fma_f32 v48, v48, v23, v31
	v_cvt_pk_bf16_f32 v48, v51, v48
	v_lshlrev_b32_e32 v51, 16, v49
	v_and_b32_e32 v49, 0xffff0000, v49
	v_sub_f32_e32 v49, v49, v52
	v_sub_f32_e32 v51, v51, v52
	v_mul_f32_e32 v49, v53, v49
	v_mul_f32_e32 v51, v53, v51
	v_fma_f32 v49, v49, v25, v33
	v_fma_f32 v51, v51, v24, v32
	v_cvt_pk_bf16_f32 v49, v51, v49
	ds_write_b128 v215, v[46:49] offset:32768
	v_lshlrev_b32_e32 v46, 3, v140
	v_add_u32_e32 v46, s5, v46
	ds_read_b64 v[46:47], v46
	v_lshlrev_b32_e32 v48, 16, v42
	v_and_b32_e32 v42, 0xffff0000, v42
	s_waitcnt lgkmcnt(0)
	v_sub_f32_e32 v48, v48, v46
	v_sub_f32_e32 v42, v42, v46
	v_mul_f32_e32 v48, v47, v48
	v_mul_f32_e32 v42, v47, v42
	v_fma_f32 v48, v48, v34, v38
	v_fma_f32 v42, v42, v35, v39
	v_cvt_pk_bf16_f32 v42, v48, v42
	v_lshlrev_b32_e32 v48, 16, v43
	v_and_b32_e32 v43, 0xffff0000, v43
	v_sub_f32_e32 v48, v48, v46
	v_sub_f32_e32 v43, v43, v46
	v_mul_f32_e32 v48, v47, v48
	v_mul_f32_e32 v43, v47, v43
	v_fma_f32 v48, v48, v36, v40
	v_fma_f32 v43, v43, v37, v41
	v_cvt_pk_bf16_f32 v43, v48, v43
	v_lshlrev_b32_e32 v48, 16, v44
	v_and_b32_e32 v44, 0xffff0000, v44
	v_sub_f32_e32 v48, v48, v46
	v_sub_f32_e32 v44, v44, v46
	v_mul_f32_e32 v48, v47, v48
	v_mul_f32_e32 v44, v47, v44
	v_fma_f32 v48, v48, v22, v30
	v_fma_f32 v44, v44, v23, v31
	v_cvt_pk_bf16_f32 v44, v48, v44
	v_lshlrev_b32_e32 v48, 16, v45
	v_and_b32_e32 v45, 0xffff0000, v45
	v_sub_f32_e32 v45, v45, v46
	v_sub_f32_e32 v48, v48, v46
	v_mul_f32_e32 v45, v47, v45
	v_mul_f32_e32 v48, v47, v48
	v_fma_f32 v45, v45, v25, v33
	v_fma_f32 v48, v48, v24, v32
	v_cvt_pk_bf16_f32 v45, v48, v45
	ds_write_b128 v216, v[42:45] offset:32768
	v_add_u32_e32 v42, s5, v0
	ds_read_b64 v[42:43], v42
	v_lshlrev_b32_e32 v44, 16, v26
	v_and_b32_e32 v26, 0xffff0000, v26
	s_waitcnt lgkmcnt(0)
	v_sub_f32_e32 v44, v44, v42
	v_sub_f32_e32 v26, v26, v42
	v_mul_f32_e32 v44, v43, v44
	v_mul_f32_e32 v26, v43, v26
	v_fma_f32 v44, v44, v34, v38
	v_fma_f32 v26, v26, v35, v39
	v_cvt_pk_bf16_f32 v26, v44, v26
	v_lshlrev_b32_e32 v44, 16, v27
	v_and_b32_e32 v27, 0xffff0000, v27
	v_sub_f32_e32 v44, v44, v42
	v_sub_f32_e32 v27, v27, v42
	v_mul_f32_e32 v44, v43, v44
	v_mul_f32_e32 v27, v43, v27
	v_fma_f32 v44, v44, v36, v40
	v_fma_f32 v27, v27, v37, v41
	v_cvt_pk_bf16_f32 v27, v44, v27
	v_lshlrev_b32_e32 v44, 16, v28
	v_and_b32_e32 v28, 0xffff0000, v28
	v_sub_f32_e32 v44, v44, v42
	v_sub_f32_e32 v28, v28, v42
	v_mul_f32_e32 v44, v43, v44
	v_mul_f32_e32 v28, v43, v28
	v_fma_f32 v44, v44, v22, v30
	v_fma_f32 v28, v28, v23, v31
	v_cvt_pk_bf16_f32 v28, v44, v28
	v_lshlrev_b32_e32 v44, 16, v29
	v_and_b32_e32 v29, 0xffff0000, v29
	v_sub_f32_e32 v29, v29, v42
	v_sub_f32_e32 v44, v44, v42
	v_mul_f32_e32 v29, v43, v29
	v_mul_f32_e32 v44, v43, v44
	v_fma_f32 v29, v29, v25, v33
	v_fma_f32 v44, v44, v24, v32
	v_cvt_pk_bf16_f32 v29, v44, v29
	ds_write_b128 v217, v[26:29] offset:32768
	v_add_u32_e32 v26, s5, v189
	ds_read_b64 v[26:27], v26
	v_lshlrev_b32_e32 v28, 16, v18
	v_and_b32_e32 v18, 0xffff0000, v18
	s_waitcnt lgkmcnt(0)
	v_sub_f32_e32 v28, v28, v26
	v_sub_f32_e32 v18, v18, v26
	v_mul_f32_e32 v28, v27, v28
	v_mul_f32_e32 v18, v27, v18
	v_fma_f32 v28, v28, v34, v38
	v_fma_f32 v18, v18, v35, v39
	v_cvt_pk_bf16_f32 v18, v28, v18
	v_lshlrev_b32_e32 v28, 16, v19
	v_and_b32_e32 v19, 0xffff0000, v19
	v_sub_f32_e32 v28, v28, v26
	v_sub_f32_e32 v19, v19, v26
	v_mul_f32_e32 v28, v27, v28
	v_mul_f32_e32 v19, v27, v19
	v_fma_f32 v28, v28, v36, v40
	v_fma_f32 v19, v19, v37, v41
	v_cvt_pk_bf16_f32 v19, v28, v19
	v_lshlrev_b32_e32 v28, 16, v20
	v_and_b32_e32 v20, 0xffff0000, v20
	v_sub_f32_e32 v28, v28, v26
	v_sub_f32_e32 v20, v20, v26
	v_mul_f32_e32 v28, v27, v28
	v_mul_f32_e32 v20, v27, v20
	v_fma_f32 v28, v28, v22, v30
	v_fma_f32 v20, v20, v23, v31
	v_cvt_pk_bf16_f32 v20, v28, v20
	v_lshlrev_b32_e32 v28, 16, v21
	v_and_b32_e32 v21, 0xffff0000, v21
	v_sub_f32_e32 v21, v21, v26
	v_sub_f32_e32 v28, v28, v26
	v_mul_f32_e32 v21, v27, v21
	v_mul_f32_e32 v28, v27, v28
	v_fma_f32 v21, v21, v25, v33
	v_fma_f32 v28, v28, v24, v32
	v_cvt_pk_bf16_f32 v21, v28, v21
	ds_write_b128 v218, v[18:21] offset:32768
	v_add_u32_e32 v18, s5, v190
	ds_read_b64 v[18:19], v18
	v_lshlrev_b32_e32 v20, 16, v14
	v_and_b32_e32 v14, 0xffff0000, v14
	v_lshlrev_b32_e32 v28, 16, v6
	v_and_b32_e32 v6, 0xffff0000, v6
	s_waitcnt lgkmcnt(0)
; #define LAS __attribute__((address_space(3)))
; __device__ __forceinline__ unsigned pk2(float lo, float hi) { unsigned r; asm("v_cvt_pk_bf16_f32 %0, %1, %2" : "=v"(r) : "v"(lo), "v"(hi)); return r; }
; __device__ __forceinline__ float bf_lo(unsigned u) { return __uint_as_float(u << 16); }
; __device__ __forceinline__ float bf_hi(unsigned u) { return __uint_as_float(u & 0xffff0000u); }
; __device__ __forceinline__ void phase_sgu(const Params& P, LAS unsigned char* lds, int layer_i) {
;     ...
;         for (int i = 0; i < 8; ++i) { const int n = tid + 512 * i, row = n >> 5, cc = n & 31, c0 = g * 256 + cc * 8;
;             const u32x4 v = gvr[i];
;             const float mu = st[2 * row], rs = st[2 * row + 1];
;             const f32x4 g0 = *(const f32x4*)(lng + c0), g1 = *(const f32x4*)(lng + c0 + 4), b0 = *(const f32x4*)(lnb + c0), b1 = *(const f32x4*)(lnb + c0 + 4);
;             u32x4 o;
;             o.x = pk2((bf_lo(v.x) - mu) * rs * g0.x + b0.x, (bf_hi(v.x) - mu) * rs * g0.y + b0.y); o.y = pk2((bf_lo(v.y) - mu) * rs * g0.z + b0.z, (bf_hi(v.y) - mu) * rs * g0.w + b0.w);
;             o.z = pk2((bf_lo(v.z) - mu) * rs * g1.x + b1.x, (bf_hi(v.z) - mu) * rs * g1.y + b1.y); o.w = pk2((bf_lo(v.w) - mu) * rs * g1.z + b1.z, (bf_hi(v.w) - mu) * rs * g1.w + b1.w);
;             *(LAS u32x4*)(lds + SG_B + (cc >> 4) * 32768 + off_b(row, cc & 15)) = o; }
	v_sub_f32_e32 v20, v20, v18
	v_sub_f32_e32 v14, v14, v18
	v_mul_f32_e32 v20, v19, v20
	v_mul_f32_e32 v14, v19, v14
	v_fma_f32 v20, v20, v34, v38
	v_fma_f32 v14, v14, v35, v39
	v_cvt_pk_bf16_f32 v14, v20, v14
	v_lshlrev_b32_e32 v20, 16, v15
	v_and_b32_e32 v15, 0xffff0000, v15
	v_sub_f32_e32 v20, v20, v18
	v_sub_f32_e32 v15, v15, v18
	v_mul_f32_e32 v20, v19, v20
	v_mul_f32_e32 v15, v19, v15
	v_fma_f32 v20, v20, v36, v40
	v_fma_f32 v15, v15, v37, v41
	v_cvt_pk_bf16_f32 v15, v20, v15
	v_lshlrev_b32_e32 v20, 16, v16
	v_and_b32_e32 v16, 0xffff0000, v16
	v_sub_f32_e32 v20, v20, v18
	v_sub_f32_e32 v16, v16, v18
	v_mul_f32_e32 v20, v19, v20
	v_mul_f32_e32 v16, v19, v16
	v_fma_f32 v20, v20, v22, v30
	v_fma_f32 v16, v16, v23, v31
	v_cvt_pk_bf16_f32 v16, v20, v16
	v_lshlrev_b32_e32 v20, 16, v17
	v_and_b32_e32 v17, 0xffff0000, v17
	v_sub_f32_e32 v17, v17, v18
	v_sub_f32_e32 v20, v20, v18
	v_mul_f32_e32 v17, v19, v17
	v_mul_f32_e32 v20, v19, v20
	v_fma_f32 v17, v17, v25, v33
	v_fma_f32 v20, v20, v24, v32
	v_cvt_pk_bf16_f32 v17, v20, v17
	ds_write_b128 v219, v[14:17] offset:32768
	v_add_u32_e32 v14, s5, v191
	ds_read_b64 v[14:15], v14
	v_lshlrev_b32_e32 v16, 16, v10
	v_and_b32_e32 v10, 0xffff0000, v10
	s_waitcnt lgkmcnt(0)
	v_sub_f32_e32 v16, v16, v14
	v_sub_f32_e32 v10, v10, v14
	v_mul_f32_e32 v16, v15, v16
	v_mul_f32_e32 v10, v15, v10
	v_fma_f32 v16, v16, v34, v38
	v_fma_f32 v10, v10, v35, v39
	v_cvt_pk_bf16_f32 v10, v16, v10
	v_lshlrev_b32_e32 v16, 16, v11
	v_sub_f32_e32 v16, v16, v14
	v_and_b32_e32 v11, 0xffff0000, v11
	v_mul_f32_e32 v16, v15, v16
	v_sub_f32_e32 v11, v11, v14
	v_fma_f32 v16, v16, v36, v40
	v_mul_f32_e32 v11, v15, v11
	v_fmac_f32_e32 v41, v11, v37
	v_cvt_pk_bf16_f32 v11, v16, v41
	v_lshlrev_b32_e32 v16, 16, v12
	v_and_b32_e32 v12, 0xffff0000, v12
	v_sub_f32_e32 v16, v16, v14
	v_sub_f32_e32 v12, v12, v14
	v_mul_f32_e32 v16, v15, v16
	v_mul_f32_e32 v12, v15, v12
	v_fma_f32 v16, v16, v22, v30
	v_fma_f32 v12, v12, v23, v31
	v_cvt_pk_bf16_f32 v12, v16, v12
	v_lshlrev_b32_e32 v16, 16, v13
	v_and_b32_e32 v13, 0xffff0000, v13
	v_sub_f32_e32 v16, v16, v14
	v_sub_f32_e32 v13, v13, v14
	v_mul_f32_e32 v16, v15, v16
	v_mul_f32_e32 v13, v15, v13
	v_fma_f32 v16, v16, v24, v32
	v_fmac_f32_e32 v33, v13, v25
	v_cvt_pk_bf16_f32 v13, v16, v33
	ds_write_b128 v220, v[10:13] offset:32768
	v_add_u32_e32 v10, s5, v192
	ds_read_b64 v[26:27], v10
	v_mov_b32_e32 v10, v100
	v_mov_b32_e32 v11, v101
	v_mov_b32_e32 v12, v102
	v_mov_b32_e32 v13, v103
	v_mov_b32_e32 v18, v104
	v_mov_b32_e32 v19, v105
	v_mov_b32_e32 v20, v106
	v_mov_b32_e32 v21, v107
	v_mov_b32_e32 v14, v108
	v_mov_b32_e32 v15, v109
	v_mov_b32_e32 v16, v110
	v_mov_b32_e32 v17, v111
	v_mov_b32_e32 v22, v112
	v_mov_b32_e32 v23, v113
	v_mov_b32_e32 v24, v114
	v_mov_b32_e32 v25, v115
	s_waitcnt lgkmcnt(0)
	v_sub_f32_e32 v28, v28, v26
	v_sub_f32_e32 v6, v6, v26
	v_mul_f32_e32 v28, v27, v28
	v_mul_f32_e32 v6, v27, v6
	s_waitcnt vmcnt(0)
	v_fma_f32 v28, v28, v18, v22
	v_fma_f32 v6, v6, v19, v23
	v_cvt_pk_bf16_f32 v6, v28, v6
	v_lshlrev_b32_e32 v28, 16, v7
	v_and_b32_e32 v7, 0xffff0000, v7
	v_sub_f32_e32 v28, v28, v26
	v_sub_f32_e32 v7, v7, v26
	v_mul_f32_e32 v28, v27, v28
	v_mul_f32_e32 v7, v27, v7
	v_fma_f32 v28, v28, v20, v24
	v_fma_f32 v7, v7, v21, v25
	v_cvt_pk_bf16_f32 v7, v28, v7
	v_lshlrev_b32_e32 v28, 16, v8
	v_and_b32_e32 v8, 0xffff0000, v8
	v_sub_f32_e32 v28, v28, v26
	v_sub_f32_e32 v8, v8, v26
	v_mul_f32_e32 v28, v27, v28
	v_mul_f32_e32 v8, v27, v8
	v_fma_f32 v28, v28, v10, v14
	v_fma_f32 v8, v8, v11, v15
	v_cvt_pk_bf16_f32 v8, v28, v8
	v_lshlrev_b32_e32 v28, 16, v9
	v_and_b32_e32 v9, 0xffff0000, v9
	v_sub_f32_e32 v9, v9, v26
	v_sub_f32_e32 v28, v28, v26
	v_mul_f32_e32 v9, v27, v9
	v_mul_f32_e32 v28, v27, v28
	v_fma_f32 v9, v9, v13, v17
	v_fma_f32 v28, v28, v12, v16
	v_cvt_pk_bf16_f32 v9, v28, v9
	ds_write_b128 v221, v[6:9] offset:32768
	v_add_u32_e32 v6, s5, v193
	ds_read_b64 v[6:7], v6
	v_lshlrev_b32_e32 v8, 16, v2
	v_and_b32_e32 v2, 0xffff0000, v2
	s_waitcnt lgkmcnt(0)
	v_sub_f32_e32 v8, v8, v6
	v_sub_f32_e32 v2, v2, v6
	v_mul_f32_e32 v8, v7, v8
	v_mul_f32_e32 v2, v7, v2
	v_fma_f32 v8, v8, v18, v22
	v_fma_f32 v2, v2, v19, v23
	v_cvt_pk_bf16_f32 v2, v8, v2
	v_lshlrev_b32_e32 v8, 16, v3
	v_sub_f32_e32 v8, v8, v6
	v_and_b32_e32 v3, 0xffff0000, v3
	v_mul_f32_e32 v8, v7, v8
	v_sub_f32_e32 v3, v3, v6
	v_fma_f32 v8, v8, v20, v24
	v_mul_f32_e32 v3, v7, v3
	v_fmac_f32_e32 v25, v3, v21
	v_cvt_pk_bf16_f32 v3, v8, v25
	v_lshlrev_b32_e32 v8, 16, v4
	v_and_b32_e32 v4, 0xffff0000, v4
	v_sub_f32_e32 v8, v8, v6
	v_sub_f32_e32 v4, v4, v6
	v_mul_f32_e32 v8, v7, v8
	v_mul_f32_e32 v4, v7, v4
	v_fma_f32 v8, v8, v10, v14
	v_fma_f32 v4, v4, v11, v15
	v_cvt_pk_bf16_f32 v4, v8, v4
	v_lshlrev_b32_e32 v8, 16, v5
	v_and_b32_e32 v5, 0xffff0000, v5
	v_sub_f32_e32 v8, v8, v6
	v_sub_f32_e32 v5, v5, v6
	v_mul_f32_e32 v8, v7, v8
	v_mul_f32_e32 v5, v7, v5
	v_fma_f32 v8, v8, v12, v16
	v_fmac_f32_e32 v17, v5, v13
	v_cvt_pk_bf16_f32 v5, v8, v17
	ds_write_b128 v222, v[2:5] offset:32768
	v_lshl_add_u64 v[2:3], v[134:135], 0, s[12:13]
	v_lshl_add_u64 v[4:5], v[2:3], 0, v[176:177]
	s_waitcnt lgkmcnt(0)
	s_barrier
; #define LAS __attribute__((address_space(3)))
; __device__ __forceinline__ u16x4 tr_read(unsigned lds_addr) { u16x4 r; asm volatile("ds_read_b64_tr_b16 %0, %1\n\ts_waitcnt lgkmcnt(0)" : "=&v"(r) : "v"(lds_addr) : "memory"); return r; }
; #define MFMA32(a, b, c) __builtin_amdgcn_mfma_f32_32x32x16_bf16((a), (b), (c), 0, 0, 0)
; __device__ __forceinline__ void phase_sgu(const Params& P, LAS unsigned char* lds, int layer_i) {
;     ...
;         u32x4 uzr[8];
; #pragma unroll
;         for (int i = 0; i < 8; ++i) { const int n = tid + 512 * i, row = n >> 5, cc = n & 31; uzr[i] = *(const u32x4*)(uz + (row0 + row) * DM + g * 256 + cc * 8); }
;         const unsigned h = lane >> 5, blk = (lane >> 4) & 1, qq = (lane & 15) >> 2, pp = lane & 3;
;         const unsigned bimg = lbase + SG_B + (wave >> 2) * 32768; const int ct = wave & 3;
;         bf16x8 bf[8];
; #pragma unroll
;         for (int ks = 0; ks < 8; ++ks) {
;             const u16x4 t0 = tr_read(bimg + off_b(16 * ks + 8 * h + qq, 4 * ct + 2 * blk + (pp >> 1)) + 8 * (pp & 1));
;             const u16x4 t1 = tr_read(bimg + off_b(16 * ks + 8 * h + 4 + qq, 4 * ct + 2 * blk + (pp >> 1)) + 8 * (pp & 1));
;             bf[ks] = cat4(t0, t1); }
;         f32x16 acc[4];
; #pragma unroll
;         for (int tt = 0; tt < 4; ++tt) {
; #pragma unroll
;             for (int i = 0; i < 16; ++i) acc[tt][i] = 0.f;
; #pragma unroll
;             for (int ks = 0; ks < 8; ++ks) { const bf16x8 af = *(const LAS bf16x8*)(lds + SG_A + off_b(32 * tt + (lane & 31), 2 * ks + h)); acc[tt] = MFMA32(af, bf[ks], acc[tt]); }
;         }
;         __syncthreads();
	global_load_dwordx4 v[82:85], v[4:5], off
	v_lshl_add_u64 v[4:5], v[2:3], 0, v[174:175]
	global_load_dwordx4 v[74:77], v[4:5], off
	v_lshl_add_u64 v[4:5], v[2:3], 0, v[172:173]
	global_load_dwordx4 v[70:73], v[4:5], off
	v_lshl_add_u64 v[4:5], v[2:3], 0, v[170:171]
	global_load_dwordx4 v[66:69], v[4:5], off
	v_lshl_add_u64 v[4:5], v[2:3], 0, v[168:169]
	global_load_dwordx4 v[90:93], v[4:5], off
	v_lshl_add_u64 v[4:5], v[2:3], 0, v[166:167]
	global_load_dwordx4 v[86:89], v[4:5], off
	v_lshl_add_u64 v[4:5], v[2:3], 0, v[164:165]
	v_lshl_add_u64 v[2:3], v[2:3], 0, v[162:163]
	global_load_dwordx4 v[78:81], v[4:5], off
	global_load_dwordx4 v[94:97], v[2:3], off
	ds_read_b64_tr_b16 v[2:3], v194
	ds_read_b64_tr_b16 v[4:5], v195
	ds_read_b64_tr_b16 v[122:123], v196
	ds_read_b64_tr_b16 v[124:125], v197
	ds_read_b64_tr_b16 v[118:119], v198
	ds_read_b64_tr_b16 v[120:121], v199
	ds_read_b64_tr_b16 v[114:115], v200
	ds_read_b64_tr_b16 v[116:117], v201
	ds_read_b64_tr_b16 v[110:111], v202
	ds_read_b64_tr_b16 v[112:113], v203
	ds_read_b64_tr_b16 v[98:99], v204
	ds_read_b64_tr_b16 v[100:101], v205
	ds_read_b64_tr_b16 v[102:103], v206
	ds_read_b64_tr_b16 v[104:105], v207
	ds_read_b64_tr_b16 v[106:107], v208
	ds_read_b64_tr_b16 v[108:109], v209
	s_waitcnt lgkmcnt(0)
	ds_read_b128 v[6:9], v223
	ds_read_b128 v[248:251], v224 offset:24576
	ds_read_b128 v[10:13], v224
	s_waitcnt lgkmcnt(1)
	v_mfma_f32_32x32x16_bf16 v[50:65], v[6:9], v[2:5], 0
	ds_read_b128 v[6:9], v225
	s_waitcnt lgkmcnt(1)
	v_mfma_f32_32x32x16_bf16 v[50:65], v[10:13], v[122:125], v[50:65]
	ds_read_b128 v[10:13], v226
	s_waitcnt lgkmcnt(1)
	v_mfma_f32_32x32x16_bf16 v[50:65], v[6:9], v[118:121], v[50:65]
	ds_read_b128 v[6:9], v227
	s_waitcnt lgkmcnt(1)
	v_mfma_f32_32x32x16_bf16 v[50:65], v[10:13], v[114:117], v[50:65]
	ds_read_b128 v[10:13], v228
	s_waitcnt lgkmcnt(1)
	v_mfma_f32_32x32x16_bf16 v[50:65], v[6:9], v[110:113], v[50:65]
	ds_read_b128 v[6:9], v229
	s_waitcnt lgkmcnt(1)
	v_mfma_f32_32x32x16_bf16 v[50:65], v[10:13], v[98:101], v[50:65]
	ds_read_b128 v[10:13], v230
	s_waitcnt lgkmcnt(1)
	v_mfma_f32_32x32x16_bf16 v[50:65], v[6:9], v[102:105], v[50:65]
	ds_read_b128 v[6:9], v223 offset:8192
	s_waitcnt lgkmcnt(1)
	v_mfma_f32_32x32x16_bf16 v[50:65], v[10:13], v[106:109], v[50:65]
	ds_read_b128 v[10:13], v224 offset:8192
	s_waitcnt lgkmcnt(1)
	v_mfma_f32_32x32x16_bf16 v[34:49], v[6:9], v[2:5], 0
	ds_read_b128 v[6:9], v225 offset:8192
	s_waitcnt lgkmcnt(1)
	v_mfma_f32_32x32x16_bf16 v[34:49], v[10:13], v[122:125], v[34:49]
	ds_read_b128 v[10:13], v226 offset:8192
	s_waitcnt lgkmcnt(1)
	v_mfma_f32_32x32x16_bf16 v[34:49], v[6:9], v[118:121], v[34:49]
	ds_read_b128 v[6:9], v227 offset:8192
	s_waitcnt lgkmcnt(1)
	v_mfma_f32_32x32x16_bf16 v[34:49], v[10:13], v[114:117], v[34:49]
	ds_read_b128 v[10:13], v228 offset:8192
	s_waitcnt lgkmcnt(1)
	v_mfma_f32_32x32x16_bf16 v[34:49], v[6:9], v[110:113], v[34:49]
	ds_read_b128 v[6:9], v229 offset:8192
	s_waitcnt lgkmcnt(1)
	v_mfma_f32_32x32x16_bf16 v[34:49], v[10:13], v[98:101], v[34:49]
	ds_read_b128 v[10:13], v230 offset:8192
	s_waitcnt lgkmcnt(1)
	v_mfma_f32_32x32x16_bf16 v[34:49], v[6:9], v[102:105], v[34:49]
	ds_read_b128 v[6:9], v223 offset:16384
	s_waitcnt lgkmcnt(1)
	v_mfma_f32_32x32x16_bf16 v[34:49], v[10:13], v[106:109], v[34:49]
	ds_read_b128 v[10:13], v224 offset:16384
	s_waitcnt lgkmcnt(1)
	v_mfma_f32_32x32x16_bf16 v[18:33], v[6:9], v[2:5], 0
	ds_read_b128 v[6:9], v225 offset:16384
	s_waitcnt lgkmcnt(1)
	v_mfma_f32_32x32x16_bf16 v[18:33], v[10:13], v[122:125], v[18:33]
	ds_read_b128 v[10:13], v226 offset:16384
	s_waitcnt lgkmcnt(1)
	v_mfma_f32_32x32x16_bf16 v[18:33], v[6:9], v[118:121], v[18:33]
	ds_read_b128 v[6:9], v227 offset:16384
	s_waitcnt lgkmcnt(1)
	v_mfma_f32_32x32x16_bf16 v[18:33], v[10:13], v[114:117], v[18:33]
	ds_read_b128 v[10:13], v228 offset:16384
	s_waitcnt lgkmcnt(1)
	v_mfma_f32_32x32x16_bf16 v[18:33], v[6:9], v[110:113], v[18:33]
	ds_read_b128 v[6:9], v229 offset:16384
	s_waitcnt lgkmcnt(1)
	v_mfma_f32_32x32x16_bf16 v[18:33], v[10:13], v[98:101], v[18:33]
	ds_read_b128 v[10:13], v230 offset:16384
	s_waitcnt lgkmcnt(1)
	v_mfma_f32_32x32x16_bf16 v[18:33], v[6:9], v[102:105], v[18:33]
	ds_read_b128 v[6:9], v223 offset:24576
	s_waitcnt lgkmcnt(1)
	v_mfma_f32_32x32x16_bf16 v[18:33], v[10:13], v[106:109], v[18:33]
	s_waitcnt lgkmcnt(0)
	v_mfma_f32_32x32x16_bf16 v[2:17], v[6:9], v[2:5], 0
	v_mfma_f32_32x32x16_bf16 v[2:17], v[248:251], v[122:125], v[2:17]
	ds_read_b128 v[122:125], v225 offset:24576
	ds_read_b128 v[248:251], v226 offset:24576
	s_waitcnt lgkmcnt(1)
	v_mfma_f32_32x32x16_bf16 v[2:17], v[122:125], v[118:121], v[2:17]
	ds_read_b128 v[118:121], v227 offset:24576
	s_waitcnt lgkmcnt(1)
	v_mfma_f32_32x32x16_bf16 v[2:17], v[248:251], v[114:117], v[2:17]
	ds_read_b128 v[114:117], v228 offset:24576
	s_waitcnt lgkmcnt(1)
	v_mfma_f32_32x32x16_bf16 v[2:17], v[118:121], v[110:113], v[2:17]
	ds_read_b128 v[110:113], v229 offset:24576
	s_waitcnt lgkmcnt(1)
	v_mfma_f32_32x32x16_bf16 v[2:17], v[114:117], v[98:101], v[2:17]
	ds_read_b128 v[98:101], v230 offset:24576
	s_waitcnt lgkmcnt(1)
	v_mfma_f32_32x32x16_bf16 v[2:17], v[110:113], v[102:105], v[2:17]
	s_waitcnt lgkmcnt(0)
	s_barrier
; #define LAS __attribute__((address_space(3)))
; __device__ __forceinline__ void phase_sgu(const Params& P, LAS unsigned char* lds, int layer_i) {
;     ...
; #pragma unroll
;         for (int tt = 0; tt < 4; ++tt)
; #pragma unroll
;             for (int i = 0; i < 16; ++i) { const int t = 32 * tt + (i & 3) + 8 * (i >> 2) + 4 * h;
;                 *(LAS float*)(lds + t * SG_MIX_STRIDE + (32 * wave + (lane & 31)) * 4) = acc[tt][i] + bs[g * 128 + t]; }
;         __syncthreads();
	v_mfma_f32_32x32x16_bf16 v[2:17], v[98:101], v[106:109], v[2:17]
	v_or_b32_e32 v98, s30, v188
	v_lshlrev_b32_e32 v98, 2, v98
	global_load_dwordx4 v[110:113], v98, s[48:49]
	global_load_dwordx4 v[114:117], v98, s[48:49] offset:32
	global_load_dwordx4 v[118:121], v98, s[48:49] offset:64
	global_load_dwordx4 v[122:125], v98, s[48:49] offset:96
	global_load_dwordx4 v[248:251], v98, s[48:49] offset:128
	s_waitcnt vmcnt(4)
	v_add_f32_e32 v50, v50, v110
	ds_write_b32 v231, v50
	v_add_f32_e32 v50, v51, v111
	ds_write_b32 v232, v50
	v_add_f32_e32 v50, v52, v112
	ds_write_b32 v232, v50 offset:1040
	v_add_f32_e32 v50, v53, v113
	ds_write_b32 v232, v50 offset:2080
	global_load_dwordx4 v[110:113], v98, s[48:49] offset:160
	s_waitcnt vmcnt(4)
	v_add_f32_e32 v50, v54, v114
	ds_write_b32 v232, v50 offset:7280
	v_add_f32_e32 v50, v55, v115
	ds_write_b32 v232, v50 offset:8320
	v_add_f32_e32 v50, v56, v116
	ds_write_b32 v232, v50 offset:9360
	v_add_f32_e32 v50, v57, v117
	ds_write_b32 v233, v50
	global_load_dwordx4 v[114:117], v98, s[48:49] offset:192
	s_waitcnt vmcnt(4)
	v_add_f32_e32 v50, v58, v118
	ds_write_b32 v233, v50 offset:5200
	v_add_f32_e32 v50, v59, v119
	ds_write_b32 v233, v50 offset:6240
	v_add_f32_e32 v50, v60, v120
	ds_write_b32 v233, v50 offset:7280
	v_add_f32_e32 v50, v61, v121
	ds_write_b32 v233, v50 offset:8320
	global_load_dwordx4 v[118:121], v98, s[48:49] offset:224
	s_waitcnt vmcnt(4)
	v_add_f32_e32 v50, v62, v122
	ds_write_b32 v233, v50 offset:13520
	v_add_f32_e32 v50, v63, v123
	ds_write_b32 v234, v50
	v_add_f32_e32 v50, v64, v124
	ds_write_b32 v234, v50 offset:1040
	v_add_f32_e32 v50, v65, v125
	ds_write_b32 v234, v50 offset:2080
	global_load_dwordx4 v[122:125], v98, s[48:49] offset:256
	s_waitcnt vmcnt(4)
	v_add_f32_e32 v34, v34, v248
	ds_write_b32 v234, v34 offset:7280
	v_add_f32_e32 v34, v35, v249
	ds_write_b32 v234, v34 offset:8320
	v_add_f32_e32 v34, v36, v250
	ds_write_b32 v234, v34 offset:9360
	v_add_f32_e32 v34, v37, v251
	ds_write_b32 v235, v34
	global_load_dwordx4 v[248:251], v98, s[48:49] offset:288
	s_waitcnt vmcnt(4)
	v_add_f32_e32 v34, v38, v110
	ds_write_b32 v235, v34 offset:5200
	v_add_f32_e32 v34, v39, v111
	ds_write_b32 v235, v34 offset:6240
	v_add_f32_e32 v34, v40, v112
	ds_write_b32 v235, v34 offset:7280
	v_add_f32_e32 v34, v41, v113
	ds_write_b32 v235, v34 offset:8320
	global_load_dwordx4 v[110:113], v98, s[48:49] offset:320
	s_waitcnt vmcnt(4)
	v_add_f32_e32 v34, v42, v114
	ds_write_b32 v235, v34 offset:13520
	v_add_f32_e32 v34, v43, v115
	ds_write_b32 v236, v34
	v_add_f32_e32 v34, v44, v116
	ds_write_b32 v236, v34 offset:1040
	v_add_f32_e32 v34, v45, v117
	ds_write_b32 v236, v34 offset:2080
	global_load_dwordx4 v[114:117], v98, s[48:49] offset:352
	s_waitcnt vmcnt(4)
	v_add_f32_e32 v34, v46, v118
	ds_write_b32 v236, v34 offset:7280
	v_add_f32_e32 v34, v47, v119
	ds_write_b32 v236, v34 offset:8320
	v_add_f32_e32 v34, v48, v120
	ds_write_b32 v236, v34 offset:9360
	v_add_f32_e32 v34, v49, v121
	ds_write_b32 v237, v34
	global_load_dwordx4 v[118:121], v98, s[48:49] offset:384
	s_waitcnt vmcnt(4)
	v_add_f32_e32 v18, v18, v122
	ds_write_b32 v237, v18 offset:5200
	v_add_f32_e32 v18, v19, v123
	ds_write_b32 v237, v18 offset:6240
	v_add_f32_e32 v18, v20, v124
	ds_write_b32 v237, v18 offset:7280
	v_add_f32_e32 v18, v21, v125
	ds_write_b32 v237, v18 offset:8320
	global_load_dwordx4 v[122:125], v98, s[48:49] offset:416
	s_waitcnt vmcnt(4)
	v_add_f32_e32 v18, v22, v248
	ds_write_b32 v237, v18 offset:13520
	v_add_f32_e32 v18, v23, v249
	ds_write_b32 v237, v18 offset:14560
	v_add_f32_e32 v18, v24, v250
	ds_write_b32 v237, v18 offset:15600
	v_add_f32_e32 v18, v25, v251
	ds_write_b32 v237, v18 offset:16640
	global_load_dwordx4 v[248:251], v98, s[48:49] offset:448
	s_waitcnt vmcnt(4)
	v_add_f32_e32 v18, v26, v110
	ds_write_b32 v237, v18 offset:21840
	v_add_f32_e32 v18, v27, v111
	ds_write_b32 v237, v18 offset:22880
	v_add_f32_e32 v18, v28, v112
	ds_write_b32 v237, v18 offset:23920
	v_add_f32_e32 v18, v29, v113
	ds_write_b32 v237, v18 offset:24960
	global_load_dwordx4 v[110:113], v98, s[48:49] offset:480
	s_waitcnt vmcnt(4)
	v_add_f32_e32 v18, v30, v114
	ds_write_b32 v237, v18 offset:30160
	v_add_f32_e32 v18, v31, v115
	ds_write_b32 v237, v18 offset:31200
	v_add_f32_e32 v18, v32, v116
	ds_write_b32 v237, v18 offset:32240
	v_add_f32_e32 v18, v33, v117
	ds_write_b32 v237, v18 offset:33280
	s_waitcnt vmcnt(3)
	v_add_f32_e32 v2, v2, v118
	ds_write_b32 v237, v2 offset:38480
	v_add_f32_e32 v2, v3, v119
	ds_write_b32 v237, v2 offset:39520
	v_add_f32_e32 v2, v4, v120
	ds_write_b32 v237, v2 offset:40560
	v_add_f32_e32 v2, v5, v121
	ds_write_b32 v237, v2 offset:41600
	s_waitcnt vmcnt(2)
	v_add_f32_e32 v2, v6, v122
	ds_write_b32 v237, v2 offset:46800
	v_add_f32_e32 v2, v7, v123
	ds_write_b32 v237, v2 offset:47840
	v_add_f32_e32 v2, v8, v124
	ds_write_b32 v237, v2 offset:48880
	v_add_f32_e32 v2, v9, v125
	ds_write_b32 v237, v2 offset:49920
	s_waitcnt vmcnt(1)
	v_add_f32_e32 v2, v10, v248
	ds_write_b32 v237, v2 offset:55120
	v_add_f32_e32 v2, v11, v249
	ds_write_b32 v237, v2 offset:56160
	v_add_f32_e32 v2, v12, v250
	ds_write_b32 v237, v2 offset:57200
	v_add_f32_e32 v2, v13, v251
	ds_write_b32 v237, v2 offset:58240
	v_lshlrev_b32_e32 v12, 16, v82
	v_lshl_add_u64 v[10:11], v[136:137], 0, s[12:13]
	s_waitcnt vmcnt(0)
	v_add_f32_e32 v2, v14, v110
	ds_write_b32 v237, v2 offset:63440
	v_add_f32_e32 v2, v15, v111
	ds_write_b32 v237, v2 offset:64480
	v_add_f32_e32 v2, v16, v112
	ds_write_b32 v237, v2 offset:65520
	v_add_f32_e32 v2, v17, v113
	ds_write_b32 v238, v2 offset:61360
	s_waitcnt lgkmcnt(0)
	s_barrier
; #define LAS __attribute__((address_space(3)))
; __device__ __forceinline__ unsigned pk2(float lo, float hi) { unsigned r; asm("v_cvt_pk_bf16_f32 %0, %1, %2" : "=v"(r) : "v"(lo), "v"(hi)); return r; }
; __device__ __forceinline__ float bf_lo(unsigned u) { return __uint_as_float(u << 16); }
; __device__ __forceinline__ float bf_hi(unsigned u) { return __uint_as_float(u & 0xffff0000u); }
; __device__ __forceinline__ void phase_sgu(const Params& P, LAS unsigned char* lds, int layer_i) {
;     ...
; #pragma unroll
;         for (int i = 0; i < 8; ++i) { const int n = tid + 512 * i, row = n >> 5, cc = n & 31;
;             const f32x4 m0 = *(const LAS f32x4*)(lds + row * SG_MIX_STRIDE + cc * 32), m1 = *(const LAS f32x4*)(lds + row * SG_MIX_STRIDE + cc * 32 + 16);
;             const size_t o = (row0 + row) * DM + g * 256 + cc * 8;
;             const u32x4 u = uzr[i];
;             u32x4 y; y.x = pk2(bf_lo(u.x) * m0.x, bf_hi(u.x) * m0.y); y.y = pk2(bf_lo(u.y) * m0.z, bf_hi(u.y) * m0.w); y.z = pk2(bf_lo(u.z) * m1.x, bf_hi(u.z) * m1.y); y.w = pk2(bf_lo(u.w) * m1.z, bf_hi(u.w) * m1.w);
;             *(u32x4*)(Y + o) = y; }
;         __syncthreads();
	ds_read_b128 v[2:5], v239
	ds_read_b128 v[6:9], v239 offset:16
	s_waitcnt lgkmcnt(1)
	v_mul_f32_e32 v2, v2, v12
	v_and_b32_e32 v12, 0xffff0000, v82
	v_mul_f32_e32 v3, v3, v12
	v_cvt_pk_bf16_f32 v2, v2, v3
	v_lshlrev_b32_e32 v3, 16, v83
	v_mul_f32_e32 v3, v4, v3
	v_and_b32_e32 v4, 0xffff0000, v83
	v_mul_f32_e32 v4, v5, v4
	v_cvt_pk_bf16_f32 v3, v3, v4
	v_lshlrev_b32_e32 v4, 16, v84
	v_and_b32_e32 v5, 0xffff0000, v84
	s_waitcnt lgkmcnt(0)
	v_mul_f32_e32 v4, v6, v4
	v_mul_f32_e32 v5, v7, v5
	v_cvt_pk_bf16_f32 v4, v4, v5
	v_lshlrev_b32_e32 v5, 16, v85
	v_and_b32_e32 v6, 0xffff0000, v85
	v_mul_f32_e32 v5, v8, v5
	v_mul_f32_e32 v6, v9, v6
	v_cvt_pk_bf16_f32 v5, v5, v6
	v_lshl_add_u64 v[6:7], v[10:11], 0, v[176:177]
	global_store_dwordx4 v[6:7], v[2:5], off
	ds_read_b128 v[2:5], v240
	ds_read_b128 v[6:9], v240 offset:16
	v_lshlrev_b32_e32 v12, 16, v74
	s_waitcnt lgkmcnt(0)
	v_mul_f32_e32 v2, v2, v12
	v_and_b32_e32 v12, 0xffff0000, v74
	v_mul_f32_e32 v3, v3, v12
	v_cvt_pk_bf16_f32 v2, v2, v3
	v_lshlrev_b32_e32 v3, 16, v75
	v_mul_f32_e32 v3, v4, v3
	v_and_b32_e32 v4, 0xffff0000, v75
	v_mul_f32_e32 v4, v5, v4
	v_cvt_pk_bf16_f32 v3, v3, v4
	v_lshlrev_b32_e32 v4, 16, v76
	v_and_b32_e32 v5, 0xffff0000, v76
	v_mul_f32_e32 v4, v6, v4
	v_mul_f32_e32 v5, v7, v5
	v_cvt_pk_bf16_f32 v4, v4, v5
	v_lshlrev_b32_e32 v5, 16, v77
	v_and_b32_e32 v6, 0xffff0000, v77
	v_mul_f32_e32 v5, v8, v5
	v_mul_f32_e32 v6, v9, v6
	v_cvt_pk_bf16_f32 v5, v5, v6
	v_lshl_add_u64 v[6:7], v[10:11], 0, v[174:175]
	global_store_dwordx4 v[6:7], v[2:5], off
	ds_read_b128 v[2:5], v241
	ds_read_b128 v[6:9], v241 offset:16
	v_lshlrev_b32_e32 v12, 16, v70
	s_waitcnt lgkmcnt(0)
	v_mul_f32_e32 v2, v2, v12
	v_and_b32_e32 v12, 0xffff0000, v70
	v_mul_f32_e32 v3, v3, v12
	v_cvt_pk_bf16_f32 v2, v2, v3
	v_lshlrev_b32_e32 v3, 16, v71
	v_mul_f32_e32 v3, v4, v3
	v_and_b32_e32 v4, 0xffff0000, v71
	v_mul_f32_e32 v4, v5, v4
	v_cvt_pk_bf16_f32 v3, v3, v4
	v_lshlrev_b32_e32 v4, 16, v72
	v_and_b32_e32 v5, 0xffff0000, v72
	v_mul_f32_e32 v4, v6, v4
	v_mul_f32_e32 v5, v7, v5
	v_cvt_pk_bf16_f32 v4, v4, v5
	v_lshlrev_b32_e32 v5, 16, v73
	v_and_b32_e32 v6, 0xffff0000, v73
	v_mul_f32_e32 v5, v8, v5
	v_mul_f32_e32 v6, v9, v6
	v_cvt_pk_bf16_f32 v5, v5, v6
	v_lshl_add_u64 v[6:7], v[10:11], 0, v[172:173]
	global_store_dwordx4 v[6:7], v[2:5], off
	ds_read_b128 v[2:5], v242
	ds_read_b128 v[6:9], v242 offset:16
	v_lshlrev_b32_e32 v12, 16, v66
	s_waitcnt lgkmcnt(0)
	v_mul_f32_e32 v2, v2, v12
	v_and_b32_e32 v12, 0xffff0000, v66
	v_mul_f32_e32 v3, v3, v12
	v_cvt_pk_bf16_f32 v2, v2, v3
	v_lshlrev_b32_e32 v3, 16, v67
	v_mul_f32_e32 v3, v4, v3
	v_and_b32_e32 v4, 0xffff0000, v67
	v_mul_f32_e32 v4, v5, v4
	v_cvt_pk_bf16_f32 v3, v3, v4
	v_lshlrev_b32_e32 v4, 16, v68
	v_and_b32_e32 v5, 0xffff0000, v68
	v_mul_f32_e32 v4, v6, v4
	v_mul_f32_e32 v5, v7, v5
	v_cvt_pk_bf16_f32 v4, v4, v5
	v_lshlrev_b32_e32 v5, 16, v69
	v_and_b32_e32 v6, 0xffff0000, v69
	v_mul_f32_e32 v5, v8, v5
	v_mul_f32_e32 v6, v9, v6
	v_cvt_pk_bf16_f32 v5, v5, v6
	v_lshl_add_u64 v[6:7], v[10:11], 0, v[170:171]
	global_store_dwordx4 v[6:7], v[2:5], off
	ds_read_b128 v[2:5], v243
	ds_read_b128 v[6:9], v243 offset:16
	v_lshlrev_b32_e32 v12, 16, v90
	s_waitcnt lgkmcnt(0)
	v_mul_f32_e32 v2, v2, v12
	v_and_b32_e32 v12, 0xffff0000, v90
	v_mul_f32_e32 v3, v3, v12
	v_cvt_pk_bf16_f32 v2, v2, v3
	v_lshlrev_b32_e32 v3, 16, v91
	v_mul_f32_e32 v3, v4, v3
	v_and_b32_e32 v4, 0xffff0000, v91
	v_mul_f32_e32 v4, v5, v4
	v_cvt_pk_bf16_f32 v3, v3, v4
	v_lshlrev_b32_e32 v4, 16, v92
	v_and_b32_e32 v5, 0xffff0000, v92
	v_mul_f32_e32 v4, v6, v4
	v_mul_f32_e32 v5, v7, v5
	v_cvt_pk_bf16_f32 v4, v4, v5
	v_lshlrev_b32_e32 v5, 16, v93
	v_and_b32_e32 v6, 0xffff0000, v93
	v_mul_f32_e32 v5, v8, v5
	v_mul_f32_e32 v6, v9, v6
	v_cvt_pk_bf16_f32 v5, v5, v6
	v_lshl_add_u64 v[6:7], v[10:11], 0, v[168:169]
	global_store_dwordx4 v[6:7], v[2:5], off
	ds_read_b128 v[2:5], v244
	ds_read_b128 v[6:9], v244 offset:16
	v_lshlrev_b32_e32 v12, 16, v86
	s_waitcnt lgkmcnt(0)
	v_mul_f32_e32 v2, v2, v12
	v_and_b32_e32 v12, 0xffff0000, v86
	v_mul_f32_e32 v3, v3, v12
	v_cvt_pk_bf16_f32 v2, v2, v3
	v_lshlrev_b32_e32 v3, 16, v87
	v_mul_f32_e32 v3, v4, v3
	v_and_b32_e32 v4, 0xffff0000, v87
	v_mul_f32_e32 v4, v5, v4
	v_cvt_pk_bf16_f32 v3, v3, v4
	v_lshlrev_b32_e32 v4, 16, v88
	v_and_b32_e32 v5, 0xffff0000, v88
	v_mul_f32_e32 v4, v6, v4
	v_mul_f32_e32 v5, v7, v5
	v_cvt_pk_bf16_f32 v4, v4, v5
	v_lshlrev_b32_e32 v5, 16, v89
	v_and_b32_e32 v6, 0xffff0000, v89
	v_mul_f32_e32 v5, v8, v5
	v_mul_f32_e32 v6, v9, v6
	v_cvt_pk_bf16_f32 v5, v5, v6
	v_lshl_add_u64 v[6:7], v[10:11], 0, v[166:167]
	global_store_dwordx4 v[6:7], v[2:5], off
	ds_read_b128 v[2:5], v245
	ds_read_b128 v[6:9], v245 offset:16
	v_lshlrev_b32_e32 v12, 16, v78
	s_waitcnt lgkmcnt(0)
	v_mul_f32_e32 v2, v2, v12
	v_and_b32_e32 v12, 0xffff0000, v78
	v_mul_f32_e32 v3, v3, v12
	v_cvt_pk_bf16_f32 v2, v2, v3
	v_lshlrev_b32_e32 v3, 16, v79
	v_mul_f32_e32 v3, v4, v3
	v_and_b32_e32 v4, 0xffff0000, v79
	v_mul_f32_e32 v4, v5, v4
	v_cvt_pk_bf16_f32 v3, v3, v4
	v_lshlrev_b32_e32 v4, 16, v80
	v_and_b32_e32 v5, 0xffff0000, v80
	v_mul_f32_e32 v4, v6, v4
	v_mul_f32_e32 v5, v7, v5
	v_cvt_pk_bf16_f32 v4, v4, v5
	v_lshlrev_b32_e32 v5, 16, v81
	v_and_b32_e32 v6, 0xffff0000, v81
	v_mul_f32_e32 v5, v8, v5
	v_mul_f32_e32 v6, v9, v6
	v_cvt_pk_bf16_f32 v5, v5, v6
	v_lshl_add_u64 v[6:7], v[10:11], 0, v[164:165]
	global_store_dwordx4 v[6:7], v[2:5], off
	ds_read_b128 v[2:5], v246
	ds_read_b128 v[6:9], v246 offset:16
	v_lshlrev_b32_e32 v12, 16, v94
	s_waitcnt lgkmcnt(0)
	v_mul_f32_e32 v2, v2, v12
	v_and_b32_e32 v12, 0xffff0000, v94
	v_mul_f32_e32 v3, v3, v12
	v_cvt_pk_bf16_f32 v2, v2, v3
	v_lshlrev_b32_e32 v3, 16, v95
	v_mul_f32_e32 v3, v4, v3
	v_and_b32_e32 v4, 0xffff0000, v95
	v_mul_f32_e32 v4, v5, v4
	v_cvt_pk_bf16_f32 v3, v3, v4
	v_lshlrev_b32_e32 v4, 16, v96
	v_and_b32_e32 v5, 0xffff0000, v96
	v_mul_f32_e32 v4, v6, v4
	v_mul_f32_e32 v5, v7, v5
	v_cvt_pk_bf16_f32 v4, v4, v5
	v_lshlrev_b32_e32 v5, 16, v97
	v_and_b32_e32 v6, 0xffff0000, v97
	v_mul_f32_e32 v5, v8, v5
	v_mul_f32_e32 v6, v9, v6
	v_cvt_pk_bf16_f32 v5, v5, v6
	v_lshl_add_u64 v[6:7], v[10:11], 0, v[162:163]
	global_store_dwordx4 v[6:7], v[2:5], off
	s_waitcnt lgkmcnt(0)
	s_barrier
	s_cbranch_scc1 .LBB0_110
; __device__ __forceinline__ void phase_sgu(const Params& P, LAS unsigned char* lds, int layer_i) {
;     ...
;     for (int item = blockIdx.x; item < (MTOK / 128) * 8; item += gridDim.x) {
;         const int cn = item >> 3, g = item & 7; const size_t row0 = (size_t)cn * 128;
;         u32x4 gvr[8];
; #pragma unroll
;         for (int i = 0; i < 8; ++i) { const int n = tid + 512 * i, row = n >> 5, cc = n & 31; gvr[i] = *(const u32x4*)(gv + (row0 + row) * DM + g * 256 + cc * 8); }
;         { const int rr = tid >> 2, part = tid & 3; const float2* sp = (const float2*)stats + (row0 + rr) * 32 + part * 8; float s1 = 0.f, s2 = 0.f;
; #pragma unroll
;           for (int i = 0; i < 8; ++i) { const float2 v = sp[i]; s1 += v.x; s2 += v.y; }
;           s1 += __shfl_xor(s1, 1); s2 += __shfl_xor(s2, 1); s1 += __shfl_xor(s1, 2); s2 += __shfl_xor(s2, 2);
;           const float mu = s1 * (1.f / DM), var = fmaxf(s2 * (1.f / DM) - mu * mu, 0.f);
;           if (part == 0) { st[2 * rr] = mu; st[2 * rr + 1] = 1.f / sqrtf(var + 1e-6f); } }
.LBB0_108:
	s_ashr_i32 s4, s16, 3
	s_ashr_i32 s5, s4, 31
	s_and_b32 s2, s16, 7
	s_lshl_b64 s[12:13], s[4:5], 7
	s_lshl_b32 s30, s2, 9
	v_lshl_add_u64 v[4:5], s[12:13], 0, v[138:139]
	v_lshl_add_u64 v[2:3], v[126:127], 0, s[30:31]
	v_lshlrev_b64 v[176:177], 12, v[4:5]
	v_lshl_add_u64 v[4:5], v[2:3], 0, v[176:177]
	global_load_dwordx4 v[46:49], v[4:5], off
	v_lshl_add_u64 v[4:5], s[12:13], 0, v[140:141]
	v_lshlrev_b64 v[174:175], 12, v[4:5]
	v_lshl_add_u64 v[4:5], v[2:3], 0, v[174:175]
	global_load_dwordx4 v[42:45], v[4:5], off
	v_lshl_add_u64 v[4:5], s[12:13], 0, v[142:143]
	v_lshlrev_b64 v[172:173], 12, v[4:5]
	v_lshl_add_u64 v[4:5], v[2:3], 0, v[172:173]
	global_load_dwordx4 v[26:29], v[4:5], off
	v_lshl_add_u64 v[4:5], s[12:13], 0, v[144:145]
	v_lshlrev_b64 v[170:171], 12, v[4:5]
	v_lshl_add_u64 v[4:5], v[2:3], 0, v[170:171]
	global_load_dwordx4 v[18:21], v[4:5], off
	v_lshl_add_u64 v[4:5], s[12:13], 0, v[146:147]
	v_lshlrev_b64 v[168:169], 12, v[4:5]
	v_lshl_add_u64 v[4:5], v[2:3], 0, v[168:169]
	global_load_dwordx4 v[14:17], v[4:5], off
	v_lshl_add_u64 v[4:5], s[12:13], 0, v[148:149]
	v_lshlrev_b64 v[166:167], 12, v[4:5]
	v_lshl_add_u64 v[4:5], v[2:3], 0, v[166:167]
	global_load_dwordx4 v[10:13], v[4:5], off
	v_lshl_add_u64 v[4:5], s[12:13], 0, v[150:151]
	v_lshlrev_b64 v[164:165], 12, v[4:5]
	v_lshl_add_u64 v[4:5], v[2:3], 0, v[164:165]
	global_load_dwordx4 v[6:9], v[4:5], off
	v_lshl_add_u64 v[4:5], s[12:13], 0, v[152:153]
	v_lshl_add_u64 v[22:23], s[12:13], 0, v[128:129]
	v_lshlrev_b64 v[162:163], 12, v[4:5]
	v_lshlrev_b64 v[22:23], 8, v[22:23]
	v_lshl_add_u64 v[2:3], v[2:3], 0, v[162:163]
	v_lshl_add_u64 v[30:31], v[130:131], 0, v[22:23]
	global_load_dwordx4 v[2:5], v[2:3], off
	global_load_dwordx4 v[66:69], v[30:31], off
	global_load_dwordx4 v[70:73], v[30:31], off offset:16
	global_load_dwordx4 v[74:77], v[30:31], off offset:32
	global_load_dwordx4 v[78:81], v[30:31], off offset:48
	s_lshl_b32 s30, s2, 7
	v_lshl_add_u64 v[98:99], s[30:31], 0, v[154:155]
	v_lshlrev_b64 v[98:99], 8, v[98:99]
	v_lshl_add_u64 v[98:99], v[132:133], 0, v[98:99]
	global_load_dwordx4 v[82:85], v[98:99], off
	v_lshl_add_u64 v[98:99], s[30:31], 0, v[156:157]
	v_lshlrev_b64 v[98:99], 8, v[98:99]
	v_lshl_add_u64 v[98:99], v[132:133], 0, v[98:99]
	global_load_dwordx4 v[86:89], v[98:99], off
	v_lshl_add_u64 v[98:99], s[30:31], 0, v[158:159]
	v_lshlrev_b64 v[98:99], 8, v[98:99]
	v_lshl_add_u64 v[98:99], v[132:133], 0, v[98:99]
	global_load_dwordx4 v[90:93], v[98:99], off
	v_lshl_add_u64 v[98:99], s[30:31], 0, v[160:161]
	v_lshlrev_b64 v[98:99], 8, v[98:99]
	v_lshl_add_u64 v[98:99], v[132:133], 0, v[98:99]
	global_load_dwordx4 v[94:97], v[98:99], off
	s_lshl_b32 s3, s2, 8
	v_or_b32_e32 v116, s3, v187
	v_lshlrev_b32_e32 v116, 2, v116
	global_load_dwordx4 v[100:103], v116, s[44:45] offset:16
	global_load_dwordx4 v[104:107], v116, s[44:45]
	global_load_dwordx4 v[108:111], v116, s[46:47] offset:16
	global_load_dwordx4 v[112:115], v116, s[46:47]
	s_waitcnt vmcnt(8)
	v_add_f32_e32 v22, 0, v66
	v_add_f32_e32 v23, 0, v67
	v_add_f32_e32 v22, v22, v68
	v_add_f32_e32 v23, v23, v69
	v_add_f32_e32 v22, v22, v70
	v_add_f32_e32 v23, v23, v71
	v_add_f32_e32 v22, v22, v72
	v_add_f32_e32 v23, v23, v73
	v_add_f32_e32 v22, v22, v74
	v_add_f32_e32 v23, v23, v75
	v_add_f32_e32 v22, v22, v76
	v_add_f32_e32 v23, v23, v77
	v_add_f32_e32 v22, v22, v78
	v_add_f32_e32 v23, v23, v79
	v_add_f32_e32 v22, v22, v80
	v_add_f32_e32 v23, v23, v81
	ds_bpermute_b32 v24, v185, v22
	s_waitcnt lgkmcnt(0)
	v_add_f32_e32 v22, v22, v24
	ds_bpermute_b32 v24, v185, v23
	s_waitcnt lgkmcnt(0)
	v_add_f32_e32 v23, v23, v24
	ds_bpermute_b32 v24, v186, v22
	ds_bpermute_b32 v25, v186, v23
	s_and_saveexec_b64 s[12:13], s[40:41]
	s_cbranch_execz .LBB0_107
	s_waitcnt lgkmcnt(1)
	v_add_f32_e32 v22, v22, v24
	v_mul_f32_e32 v22, 0x3a000000, v22
	s_waitcnt lgkmcnt(0)
	v_add_f32_e32 v23, v23, v25
	v_mul_f32_e32 v24, v22, v22
	s_mov_b32 s3, 0x3a000000
	v_fma_f32 v23, v23, s3, -v24
	v_max_f32_e32 v23, 0, v23
	v_add_f32_e32 v23, 0x358637bd, v23
	s_mov_b32 s3, 0xf800000
	v_mul_f32_e32 v24, 0x4f800000, v23
	v_cmp_gt_f32_e32 vcc, s3, v23
	s_nop 1
	v_cndmask_b32_e32 v23, v23, v24, vcc
	v_sqrt_f32_e32 v24, v23
	s_nop 0
	v_add_u32_e32 v25, -1, v24
	v_fma_f32 v30, -v25, v24, v23
	v_cmp_ge_f32_e64 s[42:43], 0, v30
	v_add_u32_e32 v30, 1, v24
	s_nop 0
	v_cndmask_b32_e64 v25, v24, v25, s[42:43]
	v_fma_f32 v24, -v30, v24, v23
	v_cmp_lt_f32_e64 s[42:43], 0, v24
	s_nop 1
	v_cndmask_b32_e64 v24, v25, v30, s[42:43]
	v_mul_f32_e32 v25, 0x37800000, v24
	v_cndmask_b32_e32 v24, v24, v25, vcc
	v_cmp_class_f32_e32 vcc, v23, v180
	s_nop 1
	v_cndmask_b32_e32 v23, v24, v23, vcc
	v_div_scale_f32 v24, s[4:5], v23, v23, 1.0
	v_rcp_f32_e32 v25, v24
	s_nop 0
	v_fma_f32 v30, -v24, v25, 1.0
	v_fmac_f32_e32 v25, v30, v25
	v_div_scale_f32 v30, vcc, 1.0, v23, 1.0
	v_mul_f32_e32 v31, v30, v25
	v_fma_f32 v32, -v24, v31, v30
	v_fmac_f32_e32 v31, v32, v25
	v_fma_f32 v24, -v24, v31, v30
	v_div_fmas_f32 v24, v24, v25, v31
	v_div_fixup_f32 v23, v24, v23, 1.0
	ds_write_b64 v210, v[22:23]
	s_branch .LBB0_107

; __device__ __forceinline__ unsigned pk2(float lo, float hi) { unsigned r; asm("v_cvt_pk_bf16_f32 %0, %1, %2" : "=v"(r) : "v"(lo), "v"(hi)); return r; }
; __device__ __forceinline__ void phase_norm(const float* xin, const _Float16* xin_h, const bf16_t* dl, _Float16* xout, const float* g, const float* mod  , bf16_t* h) {
;     ...
;             for (int j = 0; j < 8; ++j) s += (v[q][j].x * v[q][j].x + v[q][j].y * v[q][j].y) + (v[q][j].z * v[q][j].z + v[q][j].w * v[q][j].w);
;             const float rstd = 1.f / sqrtf(wave_sum(s) * (1.f / DM) + 1e-6f);
;             const float* mb = mod + (size_t)(row >> 12) * 6144;
;             u32x2* o8 = (u32x2*)(h + (size_t)row * DM) + lane;
; #pragma unroll
;             for (int j = 0; j < 8; ++j) { const int c = 4 * lane + 256 * j;
;                 const f32x4 gg = *(const f32x4*)(g + c), sh = *(const f32x4*)(mb + c), sc = *(const f32x4*)(mb + 2048 + c);
;                 const f32x4 y = v[q][j] * rstd * gg * (1.f + sc) + sh;
;                 u32x2 w; w.x = pk2(y.x, y.y); w.y = pk2(y.z, y.w); o8[64 * j] = w; } }
.LBB0_289:
	v_mov_b32_e32 v152, v60
	v_mov_b32_e32 v153, v64
	v_mov_b32_e32 v156, v58
	v_mov_b32_e32 v157, v62
	v_mov_b32_e32 v150, v61
	v_mov_b32_e32 v151, v65
	v_mov_b32_e32 v154, v59
	v_mov_b32_e32 v155, v63
	v_pk_mul_f32 v[156:157], v[156:157], v[156:157]
	v_pk_mul_f32 v[152:153], v[152:153], v[152:153]
	v_pk_fma_f32 v[154:155], v[154:155], v[154:155], v[156:157]
	v_pk_fma_f32 v[150:151], v[150:151], v[150:151], v[152:153]
	v_pk_mul_f32 v[146:147], v[146:147], v[146:147]
	v_pk_add_f32 v[150:151], v[150:151], v[154:155]
	v_pk_fma_f32 v[146:147], v[148:149], v[148:149], v[146:147]
	v_pk_add_f32 v[150:151], v[150:151], v[150:151] op_sel_hi:[0,1]
	v_pk_add_f32 v[146:147], v[146:147], v[146:147] op_sel_hi:[0,1]
	v_mul_f32_e32 v0, v50, v50
	v_mul_f32_e32 v153, v52, v52
	v_mul_f32_e32 v145, v53, v53
	v_mul_f32_e32 v150, v46, v46
	v_mul_f32_e32 v146, v47, v47
	v_mov_b32_e32 v152, v144
	v_pk_fma_f32 v[148:149], v[50:51], v[50:51], v[0:1] op_sel_hi:[1,1,0]
	v_pk_add_f32 v[146:147], v[146:147], v[150:151]
	v_mul_f32_e32 v150, v144, v144
	v_pk_add_f32 v[144:145], v[144:145], v[152:153]
	v_mul_f32_e32 v148, v48, v48
	v_mov_b32_e32 v151, v145
	v_pk_add_f32 v[144:145], v[150:151], v[148:149]
	v_pk_mul_f32 v[140:141], v[140:141], v[140:141]
	v_pk_add_f32 v[144:145], v[144:145], v[146:147]
	v_pk_fma_f32 v[140:141], v[142:143], v[142:143], v[140:141]
	v_pk_add_f32 v[144:145], v[144:145], v[144:145] op_sel_hi:[0,1]
	v_pk_add_f32 v[140:141], v[140:141], v[140:141] op_sel_hi:[0,1]
	v_mul_f32_e32 v0, v38, v38
	v_mul_f32_e32 v147, v40, v40
	v_mul_f32_e32 v139, v41, v41
	v_mul_f32_e32 v144, v34, v34
	v_mul_f32_e32 v140, v35, v35
	v_mov_b32_e32 v146, v138
	v_pk_fma_f32 v[142:143], v[38:39], v[38:39], v[0:1] op_sel_hi:[1,1,0]
	v_pk_add_f32 v[140:141], v[140:141], v[144:145]
	v_mul_f32_e32 v144, v138, v138
	v_pk_add_f32 v[138:139], v[138:139], v[146:147]
	v_mul_f32_e32 v142, v36, v36
	v_mov_b32_e32 v145, v139
	v_pk_add_f32 v[138:139], v[144:145], v[142:143]
	s_mov_b32 s2, 0xf800000
	v_pk_add_f32 v[138:139], v[138:139], v[140:141]
	global_load_dwordx4 v[142:145], v[80:81], off
	v_add_f32_e32 v0, v138, v139
	ds_bpermute_b32 v97, v79, v0
	v_lshl_add_u64 v[154:155], s[52:53], 0, v[66:67]
	s_waitcnt lgkmcnt(0)
	v_add_f32_e32 v0, v0, v97
	ds_bpermute_b32 v97, v83, v0
	s_waitcnt lgkmcnt(0)
	v_add_f32_e32 v0, v0, v97
	ds_bpermute_b32 v97, v85, v0
	s_waitcnt lgkmcnt(0)
	v_add_f32_e32 v0, v0, v97
	ds_bpermute_b32 v97, v87, v0
	s_waitcnt lgkmcnt(0)
	v_add_f32_e32 v0, v0, v97
	ds_bpermute_b32 v97, v89, v0
	s_waitcnt lgkmcnt(0)
	v_add_f32_e32 v0, v0, v97
	ds_bpermute_b32 v97, v93, v0
	s_waitcnt lgkmcnt(0)
	v_add_f32_e32 v0, v0, v97
	v_fmamk_f32 v0, v0, 0x3a000000, v181
	v_cmp_gt_f32_e32 vcc, s2, v0
	v_mul_f32_e32 v97, 0x4f800000, v0
	s_nop 0
	v_cndmask_b32_e32 v0, v0, v97, vcc
	v_sqrt_f32_e32 v97, v0
	s_nop 0
	v_add_u32_e32 v101, -1, v97
	v_fma_f32 v138, -v101, v97, v0
	v_cmp_ge_f32_e64 s[42:43], 0, v138
	v_add_u32_e32 v138, 1, v97
	s_nop 0
	v_cndmask_b32_e64 v101, v97, v101, s[42:43]
	v_fma_f32 v97, -v138, v97, v0
	v_cmp_lt_f32_e64 s[42:43], 0, v97
	s_nop 1
	v_cndmask_b32_e64 v97, v101, v138, s[42:43]
	v_mul_f32_e32 v101, 0x37800000, v97
	v_cndmask_b32_e32 v97, v97, v101, vcc
	v_cmp_class_f32_e32 vcc, v0, v180
	s_nop 1
	v_cndmask_b32_e32 v0, v97, v0, vcc
	v_div_scale_f32 v97, s[2:3], v0, v0, 1.0
	v_rcp_f32_e32 v101, v97
	s_ashr_i32 s2, s44, 12
	s_mul_hi_i32 s3, s2, 0x6000
	s_mulk_i32 s2, 0x6000
	v_fma_f32 v138, -v97, v101, 1.0
	v_fmac_f32_e32 v101, v138, v101
	v_div_scale_f32 v138, vcc, 1.0, v0, 1.0
	v_mul_f32_e32 v139, v138, v101
	v_fma_f32 v140, -v97, v139, v138
	v_fmac_f32_e32 v139, v140, v101
	s_add_u32 s26, s33, s2
	v_fma_f32 v97, -v97, v139, v138
	s_addc_u32 s27, s58, s3
	v_div_fmas_f32 v97, v97, v101, v139
	s_add_u32 s16, s26, 0x2000
	v_div_fixup_f32 v138, v97, v0, 1.0
	s_addc_u32 s17, s27, 0
	v_lshlrev_b32_e32 v0, 2, v78
	v_lshl_add_u64 v[140:141], s[26:27], 0, v[0:1]
	v_lshl_add_u64 v[150:151], s[16:17], 0, v[0:1]
	global_load_dwordx4 v[146:149], v[140:141], off
	v_pk_mul_f32 v[64:65], v[64:65], v[138:139] op_sel_hi:[1,0]
	global_load_dwordx4 v[150:153], v[150:151], off
	v_pk_mul_f32 v[62:63], v[62:63], v[138:139] op_sel_hi:[1,0]
	v_add_u32_e32 v246, 0x1000, v0
	global_load_dwordx4 v[158:161], v[80:81], off offset:1024
	global_load_dwordx4 v[162:165], v0, s[26:27] offset:1024
	global_load_dwordx4 v[166:169], v0, s[16:17] offset:1024
	global_load_dwordx4 v[170:173], v[80:81], off offset:2048
	global_load_dwordx4 v[174:177], v0, s[26:27] offset:2048
	global_load_dwordx4 v[186:189], v0, s[16:17] offset:2048
	global_load_dwordx4 v[190:193], v[80:81], off offset:3072
	global_load_dwordx4 v[194:197], v0, s[26:27] offset:3072
	global_load_dwordx4 v[198:201], v0, s[16:17] offset:3072
	global_load_dwordx4 v[202:205], v[90:91], off
	global_load_dwordx4 v[206:209], v246, s[26:27]
	global_load_dwordx4 v[210:213], v246, s[16:17]
	global_load_dwordx4 v[214:217], v[94:95], off
	global_load_dwordx4 v[218:221], v246, s[26:27] offset:1024
	global_load_dwordx4 v[222:225], v246, s[16:17] offset:1024
	global_load_dwordx4 v[226:229], v[98:99], off
	global_load_dwordx4 v[230:233], v246, s[26:27] offset:2048
	global_load_dwordx4 v[234:237], v246, s[16:17] offset:2048
	global_load_dwordx4 v[238:241], v[102:103], off
	global_load_dwordx4 v[242:245], v246, s[26:27] offset:3072
	global_load_dwordx4 v[248:251], v246, s[16:17] offset:3072
	s_waitcnt vmcnt(0)
; __device__ __forceinline__ unsigned pk2(float lo, float hi) { unsigned r; asm("v_cvt_pk_bf16_f32 %0, %1, %2" : "=v"(r) : "v"(lo), "v"(hi)); return r; }
; __device__ __forceinline__ void phase_norm(const float* xin, const _Float16* xin_h, const bf16_t* dl, _Float16* xout, const float* g, const float* mod  , bf16_t* h) {
;     ...
;             const float rstd = 1.f / sqrtf(wave_sum(s) * (1.f / DM) + 1e-6f);
;             const float* mb = mod + (size_t)(row >> 12) * 6144;
;             u32x2* o8 = (u32x2*)(h + (size_t)row * DM) + lane;
; #pragma unroll
;             for (int j = 0; j < 8; ++j) { const int c = 4 * lane + 256 * j;
;                 const f32x4 gg = *(const f32x4*)(g + c), sh = *(const f32x4*)(mb + c), sc = *(const f32x4*)(mb + 2048 + c);
;                 const f32x4 y = v[q][j] * rstd * gg * (1.f + sc) + sh;
;                 u32x2 w; w.x = pk2(y.x, y.y); w.y = pk2(y.z, y.w); o8[64 * j] = w; } }
	v_pk_mul_f32 v[64:65], v[144:145], v[64:65]
	v_pk_mul_f32 v[62:63], v[142:143], v[62:63]
	v_pk_mul_f32 v[60:61], v[60:61], v[138:139] op_sel_hi:[1,0]
	v_pk_mul_f32 v[58:59], v[58:59], v[138:139] op_sel_hi:[1,0]
	v_pk_mul_f32 v[54:55], v[54:55], v[138:139] op_sel_hi:[1,0]
	v_pk_mul_f32 v[56:57], v[56:57], v[138:139] op_sel_hi:[1,0]
	v_pk_mul_f32 v[50:51], v[50:51], v[138:139] op_sel_hi:[1,0]
	v_pk_mul_f32 v[52:53], v[52:53], v[138:139] op_sel_hi:[1,0]
	v_pk_mul_f32 v[46:47], v[46:47], v[138:139] op_sel_hi:[1,0]
	v_pk_mul_f32 v[48:49], v[48:49], v[138:139] op_sel_hi:[1,0]
	v_pk_mul_f32 v[42:43], v[42:43], v[138:139] op_sel_hi:[1,0]
	v_pk_mul_f32 v[44:45], v[44:45], v[138:139] op_sel_hi:[1,0]
	v_pk_mul_f32 v[38:39], v[38:39], v[138:139] op_sel_hi:[1,0]
	v_pk_mul_f32 v[40:41], v[40:41], v[138:139] op_sel_hi:[1,0]
	v_pk_mul_f32 v[34:35], v[34:35], v[138:139] op_sel_hi:[1,0]
	v_pk_mul_f32 v[36:37], v[36:37], v[138:139] op_sel_hi:[1,0]
	s_cmpk_gt_i32 s12, 0x3fff
	s_waitcnt lgkmcnt(0)
	v_pk_add_f32 v[142:143], v[152:153], 1.0 op_sel_hi:[1,0]
	v_pk_add_f32 v[144:145], v[150:151], 1.0 op_sel_hi:[1,0]
	v_pk_fma_f32 v[64:65], v[142:143], v[64:65], v[148:149]
	v_pk_fma_f32 v[62:63], v[144:145], v[62:63], v[146:147]
	s_nop 0
	v_cvt_pk_bf16_f32 v62, v62, v63
	v_cvt_pk_bf16_f32 v63, v64, v65
	v_add_co_u32_e32 v64, vcc, s83, v154
	s_nop 1
	v_addc_co_u32_e32 v65, vcc, 0, v155, vcc
	global_store_dwordx2 v[64:65], v[62:63], off
	v_lshlrev_b32_e32 v62, 2, v82
	v_mov_b32_e32 v63, v1
	v_lshl_add_u64 v[150:151], s[16:17], 0, v[62:63]
	v_mov_b32_e32 v142, v158
	v_mov_b32_e32 v143, v159
	v_mov_b32_e32 v144, v160
	v_mov_b32_e32 v145, v161
	v_mov_b32_e32 v146, v162
	v_mov_b32_e32 v147, v163
	v_mov_b32_e32 v148, v164
	v_mov_b32_e32 v149, v165
	v_pk_mul_f32 v[58:59], v[142:143], v[58:59]
	v_mov_b32_e32 v150, v166
	v_mov_b32_e32 v151, v167
	v_mov_b32_e32 v152, v168
	v_mov_b32_e32 v153, v169
	v_pk_mul_f32 v[60:61], v[144:145], v[60:61]
	s_waitcnt lgkmcnt(0)
	v_pk_add_f32 v[144:145], v[150:151], 1.0 op_sel_hi:[1,0]
	v_pk_add_f32 v[142:143], v[152:153], 1.0 op_sel_hi:[1,0]
	v_pk_fma_f32 v[58:59], v[144:145], v[58:59], v[146:147]
	v_pk_fma_f32 v[60:61], v[142:143], v[60:61], v[148:149]
	v_cvt_pk_bf16_f32 v58, v58, v59
	s_nop 0
	v_cvt_pk_bf16_f32 v59, v60, v61
	global_store_dwordx2 v[64:65], v[58:59], off offset:512
	v_lshlrev_b32_e32 v58, 2, v84
	v_mov_b32_e32 v59, v1
	v_lshl_add_u64 v[60:61], s[16:17], 0, v[58:59]
	v_mov_b32_e32 v142, v170
	v_mov_b32_e32 v143, v171
	v_mov_b32_e32 v144, v172
	v_mov_b32_e32 v145, v173
	v_mov_b32_e32 v146, v174
	v_mov_b32_e32 v147, v175
	v_mov_b32_e32 v148, v176
	v_mov_b32_e32 v149, v177
	v_mov_b32_e32 v150, v186
	v_mov_b32_e32 v151, v187
	v_mov_b32_e32 v152, v188
	v_mov_b32_e32 v153, v189
	v_pk_mul_f32 v[54:55], v[142:143], v[54:55]
	v_pk_mul_f32 v[56:57], v[144:145], v[56:57]
	s_waitcnt lgkmcnt(0)
	v_pk_add_f32 v[142:143], v[150:151], 1.0 op_sel_hi:[1,0]
	v_pk_add_f32 v[60:61], v[152:153], 1.0 op_sel_hi:[1,0]
	v_pk_fma_f32 v[54:55], v[142:143], v[54:55], v[146:147]
	v_pk_fma_f32 v[56:57], v[60:61], v[56:57], v[148:149]
	v_cvt_pk_bf16_f32 v54, v54, v55
	s_nop 0
	v_cvt_pk_bf16_f32 v55, v56, v57
	global_store_dwordx2 v[64:65], v[54:55], off offset:1024
	v_lshlrev_b32_e32 v54, 2, v86
	v_mov_b32_e32 v55, v1
	v_lshl_add_u64 v[56:57], s[16:17], 0, v[54:55]
	v_mov_b32_e32 v142, v190
	v_mov_b32_e32 v143, v191
	v_mov_b32_e32 v144, v192
	v_mov_b32_e32 v145, v193
	v_mov_b32_e32 v146, v194
	v_mov_b32_e32 v147, v195
	v_mov_b32_e32 v148, v196
	v_mov_b32_e32 v149, v197
	v_mov_b32_e32 v150, v198
	v_mov_b32_e32 v151, v199
	v_mov_b32_e32 v152, v200
	v_mov_b32_e32 v153, v201
	v_pk_mul_f32 v[50:51], v[50:51], v[142:143]
	v_pk_mul_f32 v[52:53], v[52:53], v[144:145]
	s_waitcnt lgkmcnt(0)
	v_pk_add_f32 v[60:61], v[150:151], 1.0 op_sel_hi:[1,0]
	v_pk_add_f32 v[56:57], v[152:153], 1.0 op_sel_hi:[1,0]
	v_pk_fma_f32 v[50:51], v[50:51], v[60:61], v[146:147]
	v_pk_fma_f32 v[52:53], v[52:53], v[56:57], v[148:149]
	v_cvt_pk_bf16_f32 v50, v50, v51
	s_nop 0
	v_cvt_pk_bf16_f32 v51, v52, v53
	global_store_dwordx2 v[64:65], v[50:51], off offset:1536
	v_lshlrev_b32_e32 v50, 2, v88
	v_mov_b32_e32 v51, v1
	v_lshl_add_u64 v[52:53], s[26:27], 0, v[50:51]
	v_mov_b32_e32 v144, v206
	v_mov_b32_e32 v145, v207
	v_mov_b32_e32 v146, v208
	v_mov_b32_e32 v147, v209
	v_lshl_add_u64 v[52:53], s[16:17], 0, v[50:51]
	v_mov_b32_e32 v140, v202
	v_mov_b32_e32 v141, v203
	v_mov_b32_e32 v142, v204
	v_mov_b32_e32 v143, v205
	v_mov_b32_e32 v148, v210
	v_mov_b32_e32 v149, v211
	v_mov_b32_e32 v150, v212
	v_mov_b32_e32 v151, v213
	v_pk_mul_f32 v[46:47], v[46:47], v[140:141]
	s_waitcnt lgkmcnt(0)
; __device__ __forceinline__ unsigned pk2(float lo, float hi) { unsigned r; asm("v_cvt_pk_bf16_f32 %0, %1, %2" : "=v"(r) : "v"(lo), "v"(hi)); return r; }
; __device__ __forceinline__ float bf_lo(unsigned u) { return __uint_as_float(u << 16); }
; __device__ __forceinline__ float bf_hi(unsigned u) { return __uint_as_float(u & 0xffff0000u); }
; __device__ __forceinline__ void phase_norm(const float* xin, const _Float16* xin_h, const bf16_t* dl, _Float16* xout, const float* g, const float* mod  , bf16_t* h) {
;     ...
;         for (int q = 0; q < 2; ++q) { const int row = row0 + q * NW; float s = 0.f;
;             if (row >= MTOK) break;
;             if (dl) {
; #pragma unroll
;                 for (int j = 0; j < 8; ++j) { v[q][j].x += bf_lo(d[q][j].x); v[q][j].y += bf_hi(d[q][j].x); v[q][j].z += bf_lo(d[q][j].y); v[q][j].w += bf_hi(d[q][j].y); } }
;     ...
; #pragma unroll
;             for (int j = 0; j < 8; ++j) { const int c = 4 * lane + 256 * j;
;                 const f32x4 gg = *(const f32x4*)(g + c), sh = *(const f32x4*)(mb + c), sc = *(const f32x4*)(mb + 2048 + c);
;                 const f32x4 y = v[q][j] * rstd * gg * (1.f + sc) + sh;
;                 u32x2 w; w.x = pk2(y.x, y.y); w.y = pk2(y.z, y.w); o8[64 * j] = w; } }
	v_pk_add_f32 v[56:57], v[148:149], 1.0 op_sel_hi:[1,0]
	v_pk_mul_f32 v[48:49], v[48:49], v[142:143]
	v_pk_add_f32 v[52:53], v[150:151], 1.0 op_sel_hi:[1,0]
	v_pk_fma_f32 v[46:47], v[46:47], v[56:57], v[144:145]
	v_pk_fma_f32 v[48:49], v[48:49], v[52:53], v[146:147]
	v_cvt_pk_bf16_f32 v46, v46, v47
	s_nop 0
	v_cvt_pk_bf16_f32 v47, v48, v49
	global_store_dwordx2 v[64:65], v[46:47], off offset:2048
	v_lshlrev_b32_e32 v46, 2, v92
	v_mov_b32_e32 v47, v1
	v_lshl_add_u64 v[48:49], s[26:27], 0, v[46:47]
	v_mov_b32_e32 v144, v218
	v_mov_b32_e32 v145, v219
	v_mov_b32_e32 v146, v220
	v_mov_b32_e32 v147, v221
	v_lshl_add_u64 v[48:49], s[16:17], 0, v[46:47]
	v_mov_b32_e32 v140, v214
	v_mov_b32_e32 v141, v215
	v_mov_b32_e32 v142, v216
	v_mov_b32_e32 v143, v217
	v_mov_b32_e32 v148, v222
	v_mov_b32_e32 v149, v223
	v_mov_b32_e32 v150, v224
	v_mov_b32_e32 v151, v225
	v_pk_mul_f32 v[42:43], v[42:43], v[140:141]
	s_waitcnt lgkmcnt(0)
	v_pk_add_f32 v[52:53], v[148:149], 1.0 op_sel_hi:[1,0]
	v_pk_mul_f32 v[44:45], v[44:45], v[142:143]
	v_pk_add_f32 v[48:49], v[150:151], 1.0 op_sel_hi:[1,0]
	v_pk_fma_f32 v[42:43], v[42:43], v[52:53], v[144:145]
	v_pk_fma_f32 v[44:45], v[44:45], v[48:49], v[146:147]
	v_cvt_pk_bf16_f32 v42, v42, v43
	s_nop 0
	v_cvt_pk_bf16_f32 v43, v44, v45
	global_store_dwordx2 v[64:65], v[42:43], off offset:2560
	v_lshlrev_b32_e32 v42, 2, v96
	v_mov_b32_e32 v43, v1
	v_lshl_add_u64 v[44:45], s[26:27], 0, v[42:43]
	v_mov_b32_e32 v144, v230
	v_mov_b32_e32 v145, v231
	v_mov_b32_e32 v146, v232
	v_mov_b32_e32 v147, v233
	v_lshl_add_u64 v[44:45], s[16:17], 0, v[42:43]
	v_mov_b32_e32 v140, v226
	v_mov_b32_e32 v141, v227
	v_mov_b32_e32 v142, v228
	v_mov_b32_e32 v143, v229
	v_mov_b32_e32 v148, v234
	v_mov_b32_e32 v149, v235
	v_mov_b32_e32 v150, v236
	v_mov_b32_e32 v151, v237
	v_pk_mul_f32 v[38:39], v[38:39], v[140:141]
	s_waitcnt lgkmcnt(0)
	v_pk_add_f32 v[48:49], v[148:149], 1.0 op_sel_hi:[1,0]
	v_pk_mul_f32 v[40:41], v[40:41], v[142:143]
	v_pk_add_f32 v[44:45], v[150:151], 1.0 op_sel_hi:[1,0]
	v_pk_fma_f32 v[38:39], v[38:39], v[48:49], v[144:145]
	v_pk_fma_f32 v[40:41], v[40:41], v[44:45], v[146:147]
	v_cvt_pk_bf16_f32 v38, v38, v39
	s_nop 0
	v_cvt_pk_bf16_f32 v39, v40, v41
	global_store_dwordx2 v[64:65], v[38:39], off offset:3072
	v_lshlrev_b32_e32 v38, 2, v100
	v_mov_b32_e32 v39, v1
	v_lshl_add_u64 v[40:41], s[26:27], 0, v[38:39]
	v_mov_b32_e32 v144, v242
	v_mov_b32_e32 v145, v243
	v_mov_b32_e32 v146, v244
	v_mov_b32_e32 v147, v245
	v_lshl_add_u64 v[40:41], s[16:17], 0, v[38:39]
	v_mov_b32_e32 v140, v238
	v_mov_b32_e32 v141, v239
	v_mov_b32_e32 v142, v240
	v_mov_b32_e32 v143, v241
	v_mov_b32_e32 v148, v248
	v_mov_b32_e32 v149, v249
	v_mov_b32_e32 v150, v250
	v_mov_b32_e32 v151, v251
	v_pk_mul_f32 v[34:35], v[34:35], v[140:141]
	s_waitcnt lgkmcnt(0)
	v_pk_add_f32 v[44:45], v[148:149], 1.0 op_sel_hi:[1,0]
	v_pk_mul_f32 v[36:37], v[36:37], v[142:143]
	v_pk_add_f32 v[40:41], v[150:151], 1.0 op_sel_hi:[1,0]
	v_pk_fma_f32 v[34:35], v[34:35], v[44:45], v[144:145]
	v_pk_fma_f32 v[36:37], v[36:37], v[40:41], v[146:147]
	v_cvt_pk_bf16_f32 v34, v34, v35
	s_nop 0
	v_cvt_pk_bf16_f32 v35, v36, v37
	global_store_dwordx2 v[64:65], v[34:35], off offset:3584
	s_cbranch_scc1 .LBB0_274
	s_and_b64 vcc, exec, s[40:41]
	s_cbranch_vccnz .LBB0_292
	v_lshlrev_b32_e32 v34, 16, v120
	v_and_b32_e32 v35, 0xffff0000, v120
	v_pk_add_f32 v[30:31], v[30:31], v[34:35]
	v_lshlrev_b32_e32 v34, 16, v121
	v_and_b32_e32 v35, 0xffff0000, v121
	v_pk_add_f32 v[32:33], v[32:33], v[34:35]
	v_lshlrev_b32_e32 v34, 16, v118
	v_and_b32_e32 v35, 0xffff0000, v118
	v_pk_add_f32 v[26:27], v[26:27], v[34:35]
	v_lshlrev_b32_e32 v34, 16, v119
	v_and_b32_e32 v35, 0xffff0000, v119
	v_pk_add_f32 v[28:29], v[28:29], v[34:35]
	v_lshlrev_b32_e32 v34, 16, v116
	v_and_b32_e32 v35, 0xffff0000, v116
	v_pk_add_f32 v[22:23], v[22:23], v[34:35]
	v_lshlrev_b32_e32 v34, 16, v117
	v_and_b32_e32 v35, 0xffff0000, v117
	v_pk_add_f32 v[24:25], v[24:25], v[34:35]
	v_lshlrev_b32_e32 v34, 16, v114
	v_and_b32_e32 v35, 0xffff0000, v114
	v_pk_add_f32 v[18:19], v[18:19], v[34:35]
	v_lshlrev_b32_e32 v34, 16, v115
	v_and_b32_e32 v35, 0xffff0000, v115
	v_pk_add_f32 v[20:21], v[20:21], v[34:35]
	v_lshlrev_b32_e32 v34, 16, v112
	v_and_b32_e32 v35, 0xffff0000, v112
	v_pk_add_f32 v[14:15], v[14:15], v[34:35]
	v_lshlrev_b32_e32 v34, 16, v113
	v_and_b32_e32 v35, 0xffff0000, v113
	v_pk_add_f32 v[16:17], v[16:17], v[34:35]
	v_lshlrev_b32_e32 v34, 16, v110
	v_and_b32_e32 v35, 0xffff0000, v110
	v_pk_add_f32 v[10:11], v[10:11], v[34:35]
	v_lshlrev_b32_e32 v34, 16, v111
	v_and_b32_e32 v35, 0xffff0000, v111
	v_pk_add_f32 v[12:13], v[12:13], v[34:35]
	v_lshlrev_b32_e32 v34, 16, v108
	v_and_b32_e32 v35, 0xffff0000, v108
	v_pk_add_f32 v[6:7], v[6:7], v[34:35]
	v_lshlrev_b32_e32 v34, 16, v109
	v_and_b32_e32 v35, 0xffff0000, v109
	v_pk_add_f32 v[8:9], v[8:9], v[34:35]
	v_lshlrev_b32_e32 v34, 16, v106
	v_and_b32_e32 v35, 0xffff0000, v106
	v_pk_add_f32 v[2:3], v[2:3], v[34:35]
	v_lshlrev_b32_e32 v34, 16, v107
	v_and_b32_e32 v35, 0xffff0000, v107
	v_pk_add_f32 v[4:5], v[4:5], v[34:35]
